# v36 with the decode-retention state-streaming units (P2 and P3) indexed by the original (XCD-striped) workgroup id
# speedup vs baseline: 1.0009x; 1.0009x over previous
; #define LAS __attribute__((address_space(3)))
; DI float bf2f(unsigned short u) { return __uint_as_float(((unsigned)u) << 16); }
; DI float gamma_of(int h) { return 1.0f - exp2f(-5.0f - (float)h); }
; DI void ret_decode_unit(LAS unsigned char* lds, const bf16_t* Z, const float* S0, float* S1, bf16_t* MIX, const float* rng, int b, int h, int tid) {
;     LAS float* qv = (LAS float*)lds; LAS float* red = qv + 768;
;     const int lane = tid & 63, wid = tid >> 6;
;     const bf16_t* zrow = Z + (size_t)(LP + b) * INW;
;     if (tid < 256) { qv[tid] = bf2f(zrow[C_RQ + h * 256 + tid]); qv[256 + tid] = bf2f(zrow[C_RK + h * 256 + tid]); qv[512 + tid] = bf2f(zrow[C_RV + h * 256 + tid]); }
;     __syncthreads();
;     const float gm = gamma_of(h);
;     const f32x4 v4 = *(const LAS f32x4*)(qv + 512 + 4 * lane);
;     f32x4 acc = {0.f, 0.f, 0.f, 0.f};
;     const size_t off = ((size_t)(b * 4 + h) * 256 + wid * 32) * 256 + 4 * lane;
;     const float* s0 = S0 + off; float* s1 = S1 + off;
; __global__ void __launch_bounds__(512, 2) fwd_kernel(Args a) {
;     ...
;     if (IN(2)) for (int rep_ = 0; rep_ < 1 + ((DUPMASK >> 2) & 1); ++rep_) { if (rep_) xcd_barrier(bar);
;         if (bx & 1) for (int u = bx; u < 256; u += G) ret_decode_unit(lds, Z, state0, out + O_SS, MIX, rng, u >> 2, u & 3, tid);
;         for (int u = bx; u < 256; u += G) ret_step1(lds, Z, KV, u >> 2, u & 3, tid);
;         if (!(bx & 1)) for (int u = bx; u < 256; u += G) ret_decode_unit(lds, Z, state0, out + O_SS, MIX, rng, u >> 2, u & 3, tid);
;     }
.LBB0_226:
	s_mov_b32 s32, s92
	s_and_b32 s98, s92, 7
	s_lshl_b32 s98, s98, 5
	s_lshr_b32 s99, s92, 3
	s_or_b32 s92, s98, s99
	s_cmp_lt_i32 s62, 3
	s_cselect_b64 s[2:3], -1, 0
	s_add_u32 s56, s60, 0x8000000
	s_addc_u32 s57, s61, 0
	s_add_u32 s4, s60, 0xfc00000
	s_addc_u32 s5, s61, 0
	v_writelane_b32 v254, s4, 23
	s_and_b64 s[10:11], s[2:3], s[0:1]
	s_andn2_b64 vcc, exec, s[10:11]
	v_writelane_b32 v254, s5, 24
	v_lshrrev_b32_e32 v252, 6, v253
	v_cmp_gt_u32_e64 s[0:1], 64, v253
	s_cbranch_vccnz .LBB0_250
	s_bitcmp0_b32 s92, 2
	v_readlane_b32 s68, v254, 7
	s_cselect_b64 s[14:15], -1, 0
	s_cmpk_gt_i32 s92, 0xff
	v_readlane_b32 s82, v254, 21
	v_lshlrev_b32_e32 v0, 2, v253
	s_cselect_b64 s[2:3], -1, 0
	v_readlane_b32 s83, v254, 22
	s_add_u32 s12, s82, 0x5220000
	v_and_b32_e32 v147, 0xfc, v0
	v_readlane_b32 s72, v254, 11
	v_readlane_b32 s73, v254, 12
	s_addc_u32 s13, s83, 0
	s_movk_i32 s4, 0x100
	v_add_u32_e32 v146, 0, v0
	v_lshlrev_b32_e32 v20, 2, v147
	v_mov_b32_e32 v21, 0
	v_lshl_add_u32 v149, v252, 7, 0
	v_mul_u32_u24_e32 v0, 0x380, v252
	s_or_b64 s[2:3], s[14:15], s[2:3]
	s_mov_b32 s17, 0
	v_add_u32_e32 v144, 0x900, v253
	v_add_u32_e32 v145, 0xd00, v253
	v_cmp_gt_u32_e64 s[6:7], s4, v253
	v_add_u32_e32 v148, 0, v20
	v_lshl_or_b32 v128, v252, 13, v147
	v_mov_b32_e32 v129, v21
	v_add3_u32 v150, v149, v0, v20
	v_lshl_add_u64 v[130:131], s[72:73], 0, v[20:21]
	s_and_b64 vcc, exec, s[2:3]
	v_readlane_b32 s69, v254, 8
	v_readlane_b32 s70, v254, 9
	v_readlane_b32 s71, v254, 10
	v_readlane_b32 s74, v254, 13
	v_readlane_b32 s75, v254, 14
	v_readlane_b32 s76, v254, 15
	v_readlane_b32 s77, v254, 16
	v_readlane_b32 s78, v254, 17
	v_readlane_b32 s79, v254, 18
	v_readlane_b32 s80, v254, 19
	v_readlane_b32 s81, v254, 20
	s_cbranch_vccnz .LBB0_236
	v_mbcnt_lo_u32_b32 v0, -1, 0
	v_mov_b32_e32 v30, 0x42800000
	v_mov_b32_e32 v31, 0x358637bd
	v_mbcnt_hi_u32_b32 v32, -1, v0
	s_mov_b32 s18, s32
	s_branch .LBB0_230
